# adds NA-lat K/V prefetch two steps ahead via alternating register sets (no copy+wait per step)
# baseline (speedup 1.0000x reference)
.LBB0_173:
	s_bitcmp1_b32 s10, 0
	s_cbranch_scc1 .Lna_pf_odd
	s_cmp_lt_i32 s10, s5
	s_cselect_b64 vcc, -1, 0
	s_and_b64 s[0:1], vcc, exec
	s_cselect_b32 s0, 0, s5
	s_sub_i32 s20, s10, s0
	v_cndmask_b32_e32 v3, v113, v111, vcc
	s_lshl_b64 s[0:1], s[20:21], 15
	v_cndmask_b32_e32 v2, v112, v110, vcc
	v_lshl_add_u64 v[2:3], v[2:3], 0, s[0:1]
	global_load_dwordx4 v[2:5], v[2:3], off
	s_cmp_ge_i32 s10, s5
	s_mov_b32 s0, s14
	s_cbranch_scc1 .LBB0_175
	s_add_i32 s0, s7, s6
	s_lshl_b32 s0, s0, 6
	s_addk_i32 s0, 0x80
.LBB0_175:
	s_ashr_i32 s1, s0, 31
	v_lshl_add_u64 v[6:7], s[0:1], 1, v[114:115]
	global_load_dwordx4 v[6:9], v[6:7], off
	s_branch .LBB0_176
.Lna_pf_odd:
	s_cmp_lt_i32 s10, s5
	s_cselect_b64 vcc, -1, 0
	s_and_b64 s[0:1], vcc, exec
	s_cselect_b32 s0, 0, s5
	s_sub_i32 s20, s10, s0
	v_cndmask_b32_e32 v97, v113, v111, vcc
	s_lshl_b64 s[0:1], s[20:21], 15
	v_cndmask_b32_e32 v96, v112, v110, vcc
	v_lshl_add_u64 v[96:97], v[96:97], 0, s[0:1]
	global_load_dwordx4 v[96:99], v[96:97], off
	s_cmp_ge_i32 s10, s5
	s_mov_b32 s0, s14
	s_cbranch_scc1 .Lna_pf_o175
	s_add_i32 s0, s7, s6
	s_lshl_b32 s0, s0, 6
	s_addk_i32 s0, 0x80
.Lna_pf_o175:
	s_ashr_i32 s1, s0, 31
	v_lshl_add_u64 v[100:101], s[0:1], 1, v[114:115]
	global_load_dwordx4 v[100:103], v[100:101], off

.LBB0_218:
	s_xor_b32 s0, s16, 1
	s_mulk_i32 s0, 0x4600
	v_add_u32_e32 v0, s0, v144
	v_add_u32_e32 v10, s0, v143
	v_add_u32_e32 v0, 0x2400, v0
	s_cmp_lt_i32 s10, s12
	s_cbranch_scc1 .Lna_w2
	s_waitcnt vmcnt(0)
	s_branch .Lna_wd
.Lna_w2:
	s_waitcnt vmcnt(2)
.Lna_wd:
	s_cmp_lg_u32 s16, 0
	s_cbranch_scc1 .Lna_w_odd
	ds_write_b128 v10, v[96:99]
	ds_write2_b64 v0, v[100:101], v[102:103] offset1:1
	s_branch .LBB0_219
.Lna_w_odd:
	ds_write_b128 v10, v[2:5]
	ds_write2_b64 v0, v[6:7], v[8:9] offset1:1
.LBB0_219:
	s_add_i32 s15, s15, 1
	s_add_i32 s9, s9, 1
	s_add_i32 s10, s10, 1
	s_add_i32 s14, s14, 64
	s_add_i32 s7, s7, 1
	s_cmp_lg_u32 s13, s15
	v_add_u32_e32 v152, 0x7c, v152
	s_waitcnt lgkmcnt(0)
	s_barrier
	s_cbranch_scc0 .LBB0_224
	s_cmp_ge_i32 s10, s12
	s_cbranch_scc0 .LBB0_173
	s_branch .LBB0_176
